# staged vmcnt waits at start of EpiResidNorm epilogues (P2,P8,P10)
# baseline (speedup 1.0000x reference)
.LBB0_232:
	v_lshl_add_u32 v64, s54, 8, v216
	v_lshl_or_b32 v140, s55, 8, v218
	v_ashrrev_i32_e32 v65, 31, v64
	v_readlane_b32 s60, v252, 0
	v_ashrrev_i32_e32 v141, 31, v140
	s_waitcnt lgkmcnt(0)
	v_lshlrev_b64 v[0:1], 13, v[64:65]
	v_readlane_b32 s61, v252, 1
	v_lshlrev_b64 v[16:17], 2, v[140:141]
	v_readlane_b32 s74, v252, 14
	v_lshl_add_u64 v[212:213], s[60:61], 0, v[0:1]
	v_lshl_add_u64 v[0:1], v[212:213], 0, v[16:17]
	v_readlane_b32 s75, v252, 15
	global_load_dwordx4 v[28:31], v[0:1], off
	global_load_dwordx4 v[40:43], v[0:1], off offset:64
	global_load_dwordx4 v[52:55], v[0:1], off offset:512
	v_lshl_add_u64 v[2:3], s[74:75], 0, v[16:17]
	global_load_dwordx4 v[12:15], v[2:3], off
	global_load_dwordx4 v[8:11], v[2:3], off offset:64
	global_load_dwordx4 v[4:7], v[2:3], off offset:512
	global_load_dwordx4 v[60:63], v[0:1], off offset:576
	v_or_b32_e32 v66, 16, v64
	v_or_b32_e32 v214, 32, v64
	v_ashrrev_i32_e32 v67, 31, v66
	v_ashrrev_i32_e32 v215, 31, v214
	v_lshlrev_b64 v[18:19], 13, v[66:67]
	v_lshlrev_b64 v[20:21], 13, v[214:215]
	v_lshl_add_u64 v[18:19], s[60:61], 0, v[18:19]
	v_lshl_add_u64 v[20:21], s[60:61], 0, v[20:21]
	global_load_dwordx4 v[0:3], v[2:3], off offset:576
	v_lshl_add_u64 v[18:19], v[18:19], 0, v[16:17]
	v_lshl_add_u64 v[16:17], v[20:21], 0, v[16:17]
	global_load_dwordx4 v[56:59], v[18:19], off
	global_load_dwordx4 v[48:51], v[18:19], off offset:64
	global_load_dwordx4 v[36:39], v[18:19], off offset:512
	global_load_dwordx4 v[24:27], v[18:19], off offset:576
	global_load_dwordx4 v[44:47], v[16:17], off
	global_load_dwordx4 v[32:35], v[16:17], off offset:64
	global_load_dwordx4 v[20:23], v[16:17], off offset:512
	s_nop 0
	global_load_dwordx4 v[16:19], v[16:17], off offset:576
	v_and_b32_e32 v225, 64, v223
	v_xor_b32_e32 v224, 16, v223
	v_add_u32_e32 v225, 64, v225
	v_xor_b32_e32 v226, 32, v223
	v_cmp_lt_i32_e32 vcc, v224, v225
	v_readlane_b32 s62, v252, 2
	v_readlane_b32 s63, v252, 3
	v_readlane_b32 s64, v252, 4
	v_readlane_b32 s65, v252, 5
	v_readlane_b32 s66, v252, 6
	v_readlane_b32 s67, v252, 7
	v_readlane_b32 s68, v252, 8
	v_readlane_b32 s69, v252, 9
	v_readlane_b32 s70, v252, 10
	v_readlane_b32 s71, v252, 11
	v_readlane_b32 s72, v252, 12
	v_readlane_b32 s73, v252, 13
	v_cndmask_b32_e32 v224, v223, v224, vcc
	v_cmp_lt_i32_e32 vcc, v226, v225
	v_readlane_b32 s60, v252, 16
	v_readlane_b32 s74, v252, 30
	v_cndmask_b32_e32 v228, v223, v226, vcc
	v_lshlrev_b64 v[226:227], 11, v[64:65]
	v_lshl_add_u64 v[226:227], v[226:227], 0, v[140:141]
	v_readlane_b32 s75, v252, 31
	v_lshlrev_b32_e32 v225, 2, v224
	v_lshlrev_b32_e32 v224, 2, v228
	v_lshl_add_u64 v[228:229], v[226:227], 2, s[74:75]
	v_lshlrev_b64 v[226:227], 1, v[226:227]
	v_lshl_add_u64 v[230:231], s[12:13], 0, v[226:227]
	v_or_b32_e32 v232, 32, v226
	v_mov_b32_e32 v233, v227
	v_lshl_add_u64 v[232:233], s[12:13], 0, v[232:233]
	v_readlane_b32 s61, v252, 17
	v_readlane_b32 s62, v252, 18
	v_readlane_b32 s63, v252, 19
	v_readlane_b32 s64, v252, 20
	v_readlane_b32 s65, v252, 21
	v_readlane_b32 s66, v252, 22
	v_readlane_b32 s67, v252, 23
	v_readlane_b32 s68, v252, 24
	v_readlane_b32 s69, v252, 25
	v_readlane_b32 s70, v252, 26
	v_readlane_b32 s71, v252, 27
	v_readlane_b32 s72, v252, 28
	v_readlane_b32 s73, v252, 29
	s_waitcnt vmcnt(8)
	v_pk_add_f32 v[30:31], v[200:201], v[30:31]
	v_pk_add_f32 v[28:29], v[202:203], v[28:29]
	v_pk_add_f32 v[42:43], v[204:205], v[42:43]
	v_pk_add_f32 v[40:41], v[206:207], v[40:41]
	v_pk_add_f32 v[54:55], v[210:211], v[54:55]
	v_pk_add_f32 v[52:53], v[208:209], v[52:53]
	v_mul_f32_e32 v234, v29, v29
	v_mul_f32_e32 v235, v31, v31
	v_pk_mul_f32 v[200:201], v[14:15], v[30:31]
	v_pk_mul_f32 v[202:203], v[12:13], v[28:29]
	v_mul_f32_e32 v236, v41, v41
	v_mul_f32_e32 v237, v43, v43
	global_store_dwordx4 v[228:229], v[28:31], off
	v_pk_mul_f32 v[204:205], v[10:11], v[42:43]
	v_pk_mul_f32 v[206:207], v[8:9], v[40:41]
	v_mul_f32_e32 v238, v53, v53
	v_mul_f32_e32 v239, v55, v55
	v_fmac_f32_e32 v234, v28, v28
	v_fmac_f32_e32 v235, v30, v30
	v_cvt_pk_bf16_f32 v28, v202, v203
	v_cvt_pk_bf16_f32 v29, v200, v201
	v_fmac_f32_e32 v236, v40, v40
	v_fmac_f32_e32 v237, v42, v42
	v_cvt_pk_bf16_f32 v30, v206, v207
	v_cvt_pk_bf16_f32 v31, v204, v205
	v_fmac_f32_e32 v238, v52, v52
	v_fmac_f32_e32 v239, v54, v54
	v_add_f32_e32 v200, v234, v235
	global_store_dwordx2 v[230:231], v[28:29], off
	global_store_dwordx4 v[228:229], v[40:43], off offset:64
	v_add_f32_e32 v28, v236, v237
	v_pk_mul_f32 v[208:209], v[6:7], v[54:55]
	v_pk_mul_f32 v[210:211], v[4:5], v[52:53]
	global_store_dwordx2 v[232:233], v[30:31], off
	global_store_dwordx4 v[228:229], v[52:55], off offset:512
	v_add_f32_e32 v29, v238, v239
	v_add_f32_e32 v28, v200, v28
	v_or_b32_e32 v30, 0x100, v226
	v_mov_b32_e32 v31, v227
	v_add_f32_e32 v40, v28, v29
	v_cvt_pk_bf16_f32 v28, v210, v211
	v_cvt_pk_bf16_f32 v29, v208, v209
	v_lshl_add_u64 v[30:31], s[12:13], 0, v[30:31]
	global_store_dwordx2 v[30:31], v[28:29], off
	v_pk_add_f32 v[30:31], v[198:199], v[62:63]
	v_pk_add_f32 v[28:29], v[196:197], v[60:61]
	v_mul_f32_e32 v42, v31, v31
	v_mul_f32_e32 v41, v29, v29
	v_fmac_f32_e32 v41, v28, v28
	v_fmac_f32_e32 v42, v30, v30
	v_add_f32_e32 v41, v41, v42
	v_add_f32_e32 v41, v40, v41
	ds_bpermute_b32 v42, v225, v41
	global_store_dwordx4 v[228:229], v[28:31], off offset:576
	v_or_b32_e32 v226, 0x120, v226
	s_nop 0
	v_pk_mul_f32 v[28:29], v[0:1], v[28:29]
	v_pk_mul_f32 v[30:31], v[2:3], v[30:31]
	v_cvt_pk_bf16_f32 v40, v28, v29
	s_waitcnt lgkmcnt(0)
	v_add_f32_e32 v28, v41, v42
	ds_bpermute_b32 v29, v224, v28
	v_cvt_pk_bf16_f32 v41, v30, v31
	v_lshl_add_u64 v[30:31], s[12:13], 0, v[226:227]
	global_store_dwordx2 v[30:31], v[40:41], off
	s_and_saveexec_b64 s[24:25], s[4:5]
	s_cbranch_execz .LBB0_234
	v_lshl_add_u64 v[30:31], v[64:65], 2, s[14:15]
	s_waitcnt lgkmcnt(0)
	v_add_f32_e32 v28, v28, v29
	global_atomic_add_f32 v[30:31], v28, off
.LBB0_234:
	s_or_b64 exec, exec, s[24:25]
	v_or_b32_e32 v196, 48, v64
	v_ashrrev_i32_e32 v197, 31, v196
	v_readlane_b32 s60, v252, 0
	s_waitcnt lgkmcnt(0)
	v_lshlrev_b64 v[28:29], 13, v[196:197]
	v_readlane_b32 s61, v252, 1
	v_readlane_b32 s62, v252, 2
	v_readlane_b32 s63, v252, 3
	v_lshl_add_u64 v[28:29], s[60:61], 0, v[28:29]
	v_lshl_add_u64 v[28:29], v[140:141], 2, v[28:29]
	global_load_dwordx4 v[60:63], v[28:29], off
	global_load_dwordx4 v[52:55], v[28:29], off offset:64
	global_load_dwordx4 v[40:43], v[28:29], off offset:512
	s_nop 0
	global_load_dwordx4 v[28:31], v[28:29], off offset:576
	v_readlane_b32 s64, v252, 4
	v_readlane_b32 s65, v252, 5
	v_readlane_b32 s66, v252, 6
	v_readlane_b32 s67, v252, 7
	v_readlane_b32 s68, v252, 8
	v_readlane_b32 s69, v252, 9
	v_readlane_b32 s70, v252, 10
	v_readlane_b32 s71, v252, 11
	v_readlane_b32 s72, v252, 12
	v_readlane_b32 s73, v252, 13
	v_readlane_b32 s74, v252, 14
	v_readlane_b32 s75, v252, 15
	v_lshlrev_b64 v[198:199], 11, v[66:67]
	v_readlane_b32 s60, v252, 16
	v_lshl_add_u64 v[198:199], v[198:199], 0, v[140:141]
	s_waitcnt vmcnt(16)
	v_pk_add_f32 v[58:59], v[194:195], v[58:59]
	v_pk_add_f32 v[56:57], v[192:193], v[56:57]
	v_readlane_b32 s74, v252, 30
	v_readlane_b32 s75, v252, 31
	v_mul_f32_e32 v65, v57, v57
	v_mul_f32_e32 v194, v59, v59
	v_lshl_add_u64 v[192:193], v[198:199], 2, s[74:75]
	global_store_dwordx4 v[192:193], v[56:59], off
	v_fmac_f32_e32 v65, v56, v56
	v_fmac_f32_e32 v194, v58, v58
	v_pk_mul_f32 v[58:59], v[14:15], v[58:59]
	v_pk_mul_f32 v[56:57], v[12:13], v[56:57]
	v_add_f32_e32 v65, v65, v194
	v_cvt_pk_bf16_f32 v56, v56, v57
	v_cvt_pk_bf16_f32 v57, v58, v59
	v_lshlrev_b64 v[58:59], 1, v[198:199]
	v_lshl_add_u64 v[194:195], s[12:13], 0, v[58:59]
	v_pk_add_f32 v[50:51], v[190:191], v[50:51]
	v_pk_add_f32 v[48:49], v[188:189], v[48:49]
	global_store_dwordx2 v[194:195], v[56:57], off
	v_mul_f32_e32 v56, v49, v49
	v_mul_f32_e32 v57, v51, v51
	global_store_dwordx4 v[192:193], v[48:51], off offset:64
	v_fmac_f32_e32 v56, v48, v48
	v_fmac_f32_e32 v57, v50, v50
	v_pk_mul_f32 v[50:51], v[10:11], v[50:51]
	v_pk_mul_f32 v[48:49], v[8:9], v[48:49]
	v_pk_add_f32 v[38:39], v[186:187], v[38:39]
	v_cvt_pk_bf16_f32 v48, v48, v49
	v_cvt_pk_bf16_f32 v49, v50, v51
	v_or_b32_e32 v50, 32, v58
	v_mov_b32_e32 v51, v59
	v_lshl_add_u64 v[50:51], s[12:13], 0, v[50:51]
	v_pk_add_f32 v[36:37], v[184:185], v[36:37]
	global_store_dwordx2 v[50:51], v[48:49], off
	v_mul_f32_e32 v48, v37, v37
	v_mul_f32_e32 v49, v39, v39
	global_store_dwordx4 v[192:193], v[36:39], off offset:512
	v_fmac_f32_e32 v48, v36, v36
	v_fmac_f32_e32 v49, v38, v38
	v_pk_mul_f32 v[38:39], v[6:7], v[38:39]
	v_pk_mul_f32 v[36:37], v[4:5], v[36:37]
	v_pk_add_f32 v[26:27], v[182:183], v[26:27]
	v_cvt_pk_bf16_f32 v36, v36, v37
	v_cvt_pk_bf16_f32 v37, v38, v39
	v_or_b32_e32 v38, 0x100, v58
	v_mov_b32_e32 v39, v59
	v_lshl_add_u64 v[38:39], s[12:13], 0, v[38:39]
	v_pk_add_f32 v[24:25], v[180:181], v[24:25]
	v_add_f32_e32 v56, v56, v57
	global_store_dwordx2 v[38:39], v[36:37], off
	v_mul_f32_e32 v36, v25, v25
	v_mul_f32_e32 v37, v27, v27
	v_add_f32_e32 v56, v65, v56
	v_add_f32_e32 v48, v48, v49
	v_fmac_f32_e32 v36, v24, v24
	v_fmac_f32_e32 v37, v26, v26
	v_add_f32_e32 v48, v56, v48
	v_add_f32_e32 v36, v36, v37
	v_add_f32_e32 v37, v48, v36
	ds_bpermute_b32 v38, v225, v37
	global_store_dwordx4 v[192:193], v[24:27], off offset:576
	v_or_b32_e32 v58, 0x120, v58
	v_readlane_b32 s61, v252, 17
	v_pk_mul_f32 v[24:25], v[0:1], v[24:25]
	v_pk_mul_f32 v[26:27], v[2:3], v[26:27]
	v_cvt_pk_bf16_f32 v36, v24, v25
	s_waitcnt lgkmcnt(0)
	v_add_f32_e32 v24, v37, v38
	ds_bpermute_b32 v25, v224, v24
	v_cvt_pk_bf16_f32 v37, v26, v27
	v_lshl_add_u64 v[26:27], s[12:13], 0, v[58:59]
	v_readlane_b32 s62, v252, 18
	v_readlane_b32 s63, v252, 19
	v_readlane_b32 s64, v252, 20
	v_readlane_b32 s65, v252, 21
	v_readlane_b32 s66, v252, 22
	v_readlane_b32 s67, v252, 23
	v_readlane_b32 s68, v252, 24
	v_readlane_b32 s69, v252, 25
	v_readlane_b32 s70, v252, 26
	v_readlane_b32 s71, v252, 27
	v_readlane_b32 s72, v252, 28
	v_readlane_b32 s73, v252, 29
	global_store_dwordx2 v[26:27], v[36:37], off
	s_and_saveexec_b64 s[24:25], s[4:5]
	s_cbranch_execz .LBB0_236
	v_lshl_add_u64 v[26:27], v[66:67], 2, s[14:15]
	s_waitcnt lgkmcnt(0)
	v_add_f32_e32 v24, v24, v25
	global_atomic_add_f32 v[26:27], v24, off
.LBB0_236:
	s_or_b64 exec, exec, s[24:25]
	v_add_u32_e32 v180, 0x80, v64
	v_ashrrev_i32_e32 v181, 31, v180
	v_readlane_b32 s60, v252, 0
	s_waitcnt lgkmcnt(0)
	v_lshlrev_b64 v[24:25], 13, v[180:181]
	v_readlane_b32 s61, v252, 1
	v_readlane_b32 s62, v252, 2
	v_readlane_b32 s63, v252, 3
	v_lshl_add_u64 v[24:25], s[60:61], 0, v[24:25]
	v_lshl_add_u64 v[24:25], v[140:141], 2, v[24:25]
	global_load_dwordx4 v[64:67], v[24:25], off
	global_load_dwordx4 v[48:51], v[24:25], off offset:64
	global_load_dwordx4 v[36:39], v[24:25], off offset:512
	s_nop 0
	global_load_dwordx4 v[24:27], v[24:25], off offset:576
	v_readlane_b32 s64, v252, 4
	v_readlane_b32 s65, v252, 5
	v_readlane_b32 s66, v252, 6
	v_readlane_b32 s67, v252, 7
	v_readlane_b32 s68, v252, 8
	v_readlane_b32 s69, v252, 9
	v_readlane_b32 s70, v252, 10
	v_readlane_b32 s71, v252, 11
	v_readlane_b32 s72, v252, 12
	v_readlane_b32 s73, v252, 13
	v_readlane_b32 s74, v252, 14
	v_readlane_b32 s75, v252, 15
	v_lshlrev_b64 v[56:57], 11, v[214:215]
	v_readlane_b32 s60, v252, 16
	v_lshl_add_u64 v[56:57], v[56:57], 0, v[140:141]
	s_waitcnt vmcnt(24)
	v_pk_add_f32 v[46:47], v[178:179], v[46:47]
	v_pk_add_f32 v[44:45], v[176:177], v[44:45]
	v_readlane_b32 s74, v252, 30
	v_readlane_b32 s75, v252, 31
	v_mul_f32_e32 v176, v45, v45
	v_mul_f32_e32 v177, v47, v47
	v_lshl_add_u64 v[58:59], v[56:57], 2, s[74:75]
	global_store_dwordx4 v[58:59], v[44:47], off
	v_fmac_f32_e32 v176, v44, v44
	v_fmac_f32_e32 v177, v46, v46
	v_pk_mul_f32 v[46:47], v[14:15], v[46:47]
	v_pk_mul_f32 v[44:45], v[12:13], v[44:45]
	v_pk_add_f32 v[34:35], v[174:175], v[34:35]
	v_cvt_pk_bf16_f32 v44, v44, v45
	v_cvt_pk_bf16_f32 v45, v46, v47
	v_lshlrev_b64 v[46:47], 1, v[56:57]
	v_lshl_add_u64 v[56:57], s[12:13], 0, v[46:47]
	v_pk_add_f32 v[32:33], v[172:173], v[32:33]
	global_store_dwordx2 v[56:57], v[44:45], off
	v_mul_f32_e32 v44, v33, v33
	v_mul_f32_e32 v45, v35, v35
	global_store_dwordx4 v[58:59], v[32:35], off offset:64
	v_fmac_f32_e32 v44, v32, v32
	v_fmac_f32_e32 v45, v34, v34
	v_pk_mul_f32 v[34:35], v[10:11], v[34:35]
	v_pk_mul_f32 v[32:33], v[8:9], v[32:33]
	v_pk_add_f32 v[22:23], v[170:171], v[22:23]
	v_cvt_pk_bf16_f32 v32, v32, v33
	v_cvt_pk_bf16_f32 v33, v34, v35
	v_or_b32_e32 v34, 32, v46
	v_mov_b32_e32 v35, v47
	v_lshl_add_u64 v[34:35], s[12:13], 0, v[34:35]
	v_pk_add_f32 v[20:21], v[168:169], v[20:21]
	global_store_dwordx2 v[34:35], v[32:33], off
	v_mul_f32_e32 v32, v21, v21
	v_mul_f32_e32 v33, v23, v23
	global_store_dwordx4 v[58:59], v[20:23], off offset:512
	v_fmac_f32_e32 v32, v20, v20
	v_fmac_f32_e32 v33, v22, v22
	v_pk_mul_f32 v[22:23], v[6:7], v[22:23]
	v_pk_mul_f32 v[20:21], v[4:5], v[20:21]
	v_pk_add_f32 v[18:19], v[166:167], v[18:19]
	v_cvt_pk_bf16_f32 v20, v20, v21
	v_cvt_pk_bf16_f32 v21, v22, v23
	v_or_b32_e32 v22, 0x100, v46
	v_mov_b32_e32 v23, v47
	v_lshl_add_u64 v[22:23], s[12:13], 0, v[22:23]
	v_pk_add_f32 v[16:17], v[164:165], v[16:17]
	v_add_f32_e32 v176, v176, v177
	v_add_f32_e32 v44, v44, v45
	global_store_dwordx2 v[22:23], v[20:21], off
	v_mul_f32_e32 v20, v17, v17
	v_mul_f32_e32 v21, v19, v19
	v_add_f32_e32 v44, v176, v44
	v_add_f32_e32 v32, v32, v33
	v_fmac_f32_e32 v20, v16, v16
	v_fmac_f32_e32 v21, v18, v18
	v_add_f32_e32 v32, v44, v32
	v_add_f32_e32 v20, v20, v21
	v_add_f32_e32 v21, v32, v20
	ds_bpermute_b32 v22, v225, v21
	global_store_dwordx4 v[58:59], v[16:19], off offset:576
	v_or_b32_e32 v46, 0x120, v46
	v_readlane_b32 s61, v252, 17
	v_pk_mul_f32 v[16:17], v[0:1], v[16:17]
	v_pk_mul_f32 v[18:19], v[2:3], v[18:19]
	v_cvt_pk_bf16_f32 v20, v16, v17
	s_waitcnt lgkmcnt(0)
	v_add_f32_e32 v16, v21, v22
	ds_bpermute_b32 v17, v224, v16
	v_cvt_pk_bf16_f32 v21, v18, v19
	v_lshl_add_u64 v[18:19], s[12:13], 0, v[46:47]
	v_readlane_b32 s62, v252, 18
	v_readlane_b32 s63, v252, 19
	v_readlane_b32 s64, v252, 20
	v_readlane_b32 s65, v252, 21
	v_readlane_b32 s66, v252, 22
	v_readlane_b32 s67, v252, 23
	v_readlane_b32 s68, v252, 24
	v_readlane_b32 s69, v252, 25
	v_readlane_b32 s70, v252, 26
	v_readlane_b32 s71, v252, 27
	v_readlane_b32 s72, v252, 28
	v_readlane_b32 s73, v252, 29
	global_store_dwordx2 v[18:19], v[20:21], off
	s_and_saveexec_b64 s[24:25], s[4:5]
	s_cbranch_execz .LBB0_238
	v_lshl_add_u64 v[18:19], v[214:215], 2, s[14:15]
	s_waitcnt lgkmcnt(0)
	v_add_f32_e32 v16, v16, v17
	global_atomic_add_f32 v[18:19], v16, off

.LBB0_852:
	v_lshl_add_u32 v200, s54, 8, v206
	v_readlane_b32 s60, v252, 16
	v_lshl_or_b32 v188, s55, 8, v208
	v_ashrrev_i32_e32 v201, 31, v200
	v_readlane_b32 s74, v252, 30
	v_readlane_b32 s75, v252, 31
	v_ashrrev_i32_e32 v189, 31, v188
	v_lshlrev_b64 v[112:113], 13, v[200:201]
	v_readlane_b32 s72, v252, 28
	v_readlane_b32 s73, v252, 29
	s_mov_b64 s[82:83], s[74:75]
	v_lshlrev_b64 v[144:145], 2, v[188:189]
	v_readlane_b32 s61, v252, 17
	v_readlane_b32 s62, v252, 18
	v_readlane_b32 s63, v252, 19
	v_readlane_b32 s64, v252, 20
	v_readlane_b32 s65, v252, 21
	v_readlane_b32 s66, v252, 22
	v_readlane_b32 s67, v252, 23
	v_readlane_b32 s68, v252, 24
	v_readlane_b32 s69, v252, 25
	v_readlane_b32 s70, v252, 26
	v_readlane_b32 s71, v252, 27
	v_lshl_add_u64 v[190:191], s[82:83], 0, v[112:113]
	s_mov_b64 s[80:81], s[72:73]
	v_lshl_add_u64 v[230:231], v[190:191], 0, v[144:145]
	v_readlane_b32 s60, v252, 32
	global_load_dwordx4 v[196:199], v[230:231], off
	global_load_dwordx4 v[216:219], v[230:231], off offset:64
	global_load_dwordx4 v[222:225], v[230:231], off offset:512
	v_readlane_b32 s74, v252, 46
	v_readlane_b32 s75, v252, 47
	v_or_b32_e32 v202, 16, v200
	v_or_b32_e32 v192, 32, v200
	v_lshl_add_u64 v[112:113], s[74:75], 0, v[144:145]
	global_load_dwordx4 v[128:131], v[112:113], off
	global_load_dwordx4 v[120:123], v[112:113], off offset:64
	global_load_dwordx4 v[116:119], v[112:113], off offset:512
	global_load_dwordx4 v[226:229], v[230:231], off offset:576
	v_ashrrev_i32_e32 v203, 31, v202
	v_ashrrev_i32_e32 v193, 31, v192
	v_lshlrev_b64 v[146:147], 13, v[202:203]
	v_lshlrev_b64 v[148:149], 13, v[192:193]
	v_lshl_add_u64 v[146:147], s[82:83], 0, v[146:147]
	global_load_dwordx4 v[112:115], v[112:113], off offset:576
	v_lshl_add_u64 v[148:149], s[82:83], 0, v[148:149]
	v_lshl_add_u64 v[204:205], v[146:147], 0, v[144:145]
	v_lshl_add_u64 v[194:195], v[148:149], 0, v[144:145]
	global_load_dwordx4 v[172:175], v[204:205], off
	global_load_dwordx4 v[168:171], v[204:205], off offset:64
	global_load_dwordx4 v[164:167], v[204:205], off offset:512
	global_load_dwordx4 v[160:163], v[204:205], off offset:576
	global_load_dwordx4 v[156:159], v[194:195], off
	global_load_dwordx4 v[152:155], v[194:195], off offset:64
	global_load_dwordx4 v[148:151], v[194:195], off offset:512
	global_load_dwordx4 v[144:147], v[194:195], off offset:576
	v_and_b32_e32 v214, 64, v212
	v_xor_b32_e32 v213, 16, v212
	v_add_u32_e32 v214, 64, v214
	v_xor_b32_e32 v215, 32, v212
	v_cmp_lt_i32_e32 vcc, v213, v214
	v_lshlrev_b64 v[232:233], 11, v[200:201]
	v_lshl_add_u64 v[232:233], v[232:233], 0, v[188:189]
	v_cndmask_b32_e32 v213, v212, v213, vcc
	v_cmp_lt_i32_e32 vcc, v215, v214
	v_lshlrev_b32_e32 v214, 2, v213
	v_lshlrev_b64 v[232:233], 1, v[232:233]
	v_cndmask_b32_e32 v215, v212, v215, vcc
	v_lshlrev_b32_e32 v213, 2, v215
	v_lshl_add_u64 v[234:235], s[14:15], 0, v[232:233]
	v_or_b32_e32 v236, 32, v232
	v_mov_b32_e32 v237, v233
	v_lshl_add_u64 v[236:237], s[14:15], 0, v[236:237]
	v_readlane_b32 s61, v252, 33
	v_readlane_b32 s62, v252, 34
	v_readlane_b32 s63, v252, 35
	v_readlane_b32 s64, v252, 36
	v_readlane_b32 s65, v252, 37
	v_readlane_b32 s66, v252, 38
	v_readlane_b32 s67, v252, 39
	v_readlane_b32 s68, v252, 40
	v_readlane_b32 s69, v252, 41
	v_readlane_b32 s70, v252, 42
	v_readlane_b32 s71, v252, 43
	v_readlane_b32 s72, v252, 44
	v_readlane_b32 s73, v252, 45
	s_waitcnt vmcnt(8)
	v_pk_add_f32 v[138:139], v[138:139], v[198:199]
	v_pk_add_f32 v[136:137], v[136:137], v[196:197]
	v_pk_add_f32 v[142:143], v[142:143], v[218:219]
	v_pk_add_f32 v[140:141], v[140:141], v[216:217]
	v_pk_add_f32 v[134:135], v[134:135], v[224:225]
	v_pk_add_f32 v[132:133], v[132:133], v[222:223]
	v_mul_f32_e32 v215, v137, v137
	v_mul_f32_e32 v221, v139, v139
	v_pk_mul_f32 v[196:197], v[130:131], v[138:139]
	v_pk_mul_f32 v[198:199], v[128:129], v[136:137]
	v_mul_f32_e32 v238, v141, v141
	v_mul_f32_e32 v239, v143, v143
	global_store_dwordx4 v[230:231], v[136:139], off
	v_pk_mul_f32 v[216:217], v[122:123], v[142:143]
	v_pk_mul_f32 v[218:219], v[120:121], v[140:141]
	v_mul_f32_e32 v240, v133, v133
	v_mul_f32_e32 v241, v135, v135
	v_fmac_f32_e32 v215, v136, v136
	v_fmac_f32_e32 v221, v138, v138
	v_cvt_pk_bf16_f32 v136, v198, v199
	v_cvt_pk_bf16_f32 v137, v196, v197
	v_fmac_f32_e32 v238, v140, v140
	v_fmac_f32_e32 v239, v142, v142
	v_cvt_pk_bf16_f32 v138, v218, v219
	v_cvt_pk_bf16_f32 v139, v216, v217
	v_fmac_f32_e32 v240, v132, v132
	v_fmac_f32_e32 v241, v134, v134
	v_add_f32_e32 v197, v215, v221
	global_store_dwordx2 v[234:235], v[136:137], off
	global_store_dwordx4 v[230:231], v[140:143], off offset:64
	v_add_f32_e32 v136, v238, v239
	v_pk_mul_f32 v[224:225], v[116:117], v[132:133]
	global_store_dwordx2 v[236:237], v[138:139], off
	global_store_dwordx4 v[230:231], v[132:135], off offset:512
	v_pk_mul_f32 v[222:223], v[118:119], v[134:135]
	v_cvt_pk_bf16_f32 v196, v224, v225
	v_add_f32_e32 v132, v240, v241
	v_add_f32_e32 v133, v197, v136
	v_add_f32_e32 v134, v133, v132
	v_or_b32_e32 v132, 0x100, v232
	v_mov_b32_e32 v133, v233
	v_cvt_pk_bf16_f32 v197, v222, v223
	v_lshl_add_u64 v[132:133], s[14:15], 0, v[132:133]
	v_pk_add_f32 v[126:127], v[126:127], v[228:229]
	v_pk_add_f32 v[124:125], v[124:125], v[226:227]
	global_store_dwordx2 v[132:133], v[196:197], off
	v_mul_f32_e32 v132, v125, v125
	v_mul_f32_e32 v133, v127, v127
	v_fmac_f32_e32 v132, v124, v124
	v_fmac_f32_e32 v133, v126, v126
	v_add_f32_e32 v132, v132, v133
	v_add_f32_e32 v133, v134, v132
	ds_bpermute_b32 v134, v214, v133
	global_store_dwordx4 v[230:231], v[124:127], off offset:576
	v_or_b32_e32 v232, 0x120, v232
	s_nop 0
	v_pk_mul_f32 v[124:125], v[112:113], v[124:125]
	v_pk_mul_f32 v[126:127], v[114:115], v[126:127]
	v_cvt_pk_bf16_f32 v132, v124, v125
	s_waitcnt lgkmcnt(0)
	v_add_f32_e32 v124, v133, v134
	ds_bpermute_b32 v125, v213, v124
	v_cvt_pk_bf16_f32 v133, v126, v127
	v_lshl_add_u64 v[126:127], s[14:15], 0, v[232:233]
	global_store_dwordx2 v[126:127], v[132:133], off
	s_and_saveexec_b64 s[28:29], s[2:3]
	s_cbranch_execz .LBB0_854
	v_lshl_add_u64 v[126:127], v[200:201], 2, s[16:17]
	s_waitcnt lgkmcnt(0)
	v_add_f32_e32 v124, v124, v125
	global_atomic_add_f32 v[126:127], v124, off
.LBB0_854:
	s_or_b64 exec, exec, s[28:29]
	v_or_b32_e32 v196, 48, v200
	v_ashrrev_i32_e32 v197, 31, v196
	v_readlane_b32 s60, v252, 16
	s_waitcnt lgkmcnt(0)
	v_lshlrev_b64 v[124:125], 13, v[196:197]
	v_readlane_b32 s74, v252, 30
	v_readlane_b32 s75, v252, 31
	s_waitcnt vmcnt(12)
	v_pk_add_f32 v[110:111], v[110:111], v[174:175]
	v_pk_add_f32 v[108:109], v[108:109], v[172:173]
	v_lshl_add_u64 v[124:125], s[74:75], 0, v[124:125]
	v_lshl_add_u64 v[198:199], v[188:189], 2, v[124:125]
	global_load_dwordx4 v[140:143], v[198:199], off
	global_load_dwordx4 v[136:139], v[198:199], off offset:64
	global_load_dwordx4 v[132:135], v[198:199], off offset:512
	global_load_dwordx4 v[124:127], v[198:199], off offset:576
	v_lshlrev_b64 v[216:217], 11, v[202:203]
	v_mul_f32_e32 v172, v109, v109
	v_mul_f32_e32 v173, v111, v111
	v_lshl_add_u64 v[216:217], v[216:217], 0, v[188:189]
	global_store_dwordx4 v[204:205], v[108:111], off
	v_fmac_f32_e32 v172, v108, v108
	v_fmac_f32_e32 v173, v110, v110
	v_pk_mul_f32 v[110:111], v[130:131], v[110:111]
	v_pk_mul_f32 v[108:109], v[128:129], v[108:109]
	v_add_f32_e32 v174, v172, v173
	v_cvt_pk_bf16_f32 v108, v108, v109
	v_cvt_pk_bf16_f32 v109, v110, v111
	v_lshlrev_b64 v[110:111], 1, v[216:217]
	v_lshl_add_u64 v[172:173], s[14:15], 0, v[110:111]
	v_pk_add_f32 v[106:107], v[106:107], v[170:171]
	v_pk_add_f32 v[104:105], v[104:105], v[168:169]
	global_store_dwordx2 v[172:173], v[108:109], off
	v_mul_f32_e32 v108, v105, v105
	v_mul_f32_e32 v109, v107, v107
	global_store_dwordx4 v[204:205], v[104:107], off offset:64
	v_fmac_f32_e32 v108, v104, v104
	v_fmac_f32_e32 v109, v106, v106
	v_pk_mul_f32 v[106:107], v[122:123], v[106:107]
	v_pk_mul_f32 v[104:105], v[120:121], v[104:105]
	v_pk_add_f32 v[102:103], v[102:103], v[166:167]
	v_cvt_pk_bf16_f32 v104, v104, v105
	v_cvt_pk_bf16_f32 v105, v106, v107
	v_or_b32_e32 v106, 32, v110
	v_mov_b32_e32 v107, v111
	v_lshl_add_u64 v[106:107], s[14:15], 0, v[106:107]
	v_pk_add_f32 v[100:101], v[100:101], v[164:165]
	global_store_dwordx2 v[106:107], v[104:105], off
	v_mul_f32_e32 v104, v101, v101
	v_mul_f32_e32 v105, v103, v103
	global_store_dwordx4 v[204:205], v[100:103], off offset:512
	v_fmac_f32_e32 v104, v100, v100
	v_fmac_f32_e32 v105, v102, v102
	v_pk_mul_f32 v[102:103], v[118:119], v[102:103]
	v_pk_mul_f32 v[100:101], v[116:117], v[100:101]
	v_pk_add_f32 v[98:99], v[98:99], v[162:163]
	v_cvt_pk_bf16_f32 v100, v100, v101
	v_cvt_pk_bf16_f32 v101, v102, v103
	v_or_b32_e32 v102, 0x100, v110
	v_mov_b32_e32 v103, v111
	v_lshl_add_u64 v[102:103], s[14:15], 0, v[102:103]
	v_pk_add_f32 v[96:97], v[96:97], v[160:161]
	v_add_f32_e32 v108, v108, v109
	global_store_dwordx2 v[102:103], v[100:101], off
	v_mul_f32_e32 v100, v97, v97
	v_mul_f32_e32 v101, v99, v99
	v_add_f32_e32 v108, v174, v108
	v_add_f32_e32 v104, v104, v105
	v_fmac_f32_e32 v100, v96, v96
	v_fmac_f32_e32 v101, v98, v98
	v_add_f32_e32 v104, v108, v104
	v_add_f32_e32 v100, v100, v101
	v_add_f32_e32 v101, v104, v100
	ds_bpermute_b32 v102, v214, v101
	global_store_dwordx4 v[204:205], v[96:99], off offset:576
	v_or_b32_e32 v110, 0x120, v110
	v_readlane_b32 s61, v252, 17
	v_pk_mul_f32 v[96:97], v[112:113], v[96:97]
	v_pk_mul_f32 v[98:99], v[114:115], v[98:99]
	v_cvt_pk_bf16_f32 v100, v96, v97
	s_waitcnt lgkmcnt(0)
	v_add_f32_e32 v96, v101, v102
	ds_bpermute_b32 v97, v213, v96
	v_cvt_pk_bf16_f32 v101, v98, v99
	v_lshl_add_u64 v[98:99], s[14:15], 0, v[110:111]
	v_readlane_b32 s62, v252, 18
	v_readlane_b32 s63, v252, 19
	v_readlane_b32 s64, v252, 20
	v_readlane_b32 s65, v252, 21
	v_readlane_b32 s66, v252, 22
	v_readlane_b32 s67, v252, 23
	v_readlane_b32 s68, v252, 24
	v_readlane_b32 s69, v252, 25
	v_readlane_b32 s70, v252, 26
	v_readlane_b32 s71, v252, 27
	v_readlane_b32 s72, v252, 28
	v_readlane_b32 s73, v252, 29
	global_store_dwordx2 v[98:99], v[100:101], off
	s_and_saveexec_b64 s[28:29], s[2:3]
	s_cbranch_execz .LBB0_856
	v_lshl_add_u64 v[98:99], v[202:203], 2, s[16:17]
	s_waitcnt lgkmcnt(0)
	v_add_f32_e32 v96, v96, v97
	global_atomic_add_f32 v[98:99], v96, off
.LBB0_856:
	s_or_b64 exec, exec, s[28:29]
	v_add_u32_e32 v160, 0x80, v200
	v_ashrrev_i32_e32 v161, 31, v160
	v_readlane_b32 s60, v252, 16
	s_waitcnt lgkmcnt(0)
	v_lshlrev_b64 v[96:97], 13, v[160:161]
	v_readlane_b32 s74, v252, 30
	v_readlane_b32 s75, v252, 31
	s_waitcnt vmcnt(20)
	v_pk_add_f32 v[94:95], v[94:95], v[158:159]
	v_pk_add_f32 v[92:93], v[92:93], v[156:157]
	v_lshl_add_u64 v[96:97], s[74:75], 0, v[96:97]
	v_lshl_add_u64 v[162:163], v[188:189], 2, v[96:97]
	global_load_dwordx4 v[108:111], v[162:163], off
	global_load_dwordx4 v[104:107], v[162:163], off offset:64
	global_load_dwordx4 v[100:103], v[162:163], off offset:512
	global_load_dwordx4 v[96:99], v[162:163], off offset:576
	v_lshlrev_b64 v[164:165], 11, v[192:193]
	v_mul_f32_e32 v156, v93, v93
	v_mul_f32_e32 v157, v95, v95
	v_lshl_add_u64 v[164:165], v[164:165], 0, v[188:189]
	global_store_dwordx4 v[194:195], v[92:95], off
	v_fmac_f32_e32 v156, v92, v92
	v_fmac_f32_e32 v157, v94, v94
	v_pk_mul_f32 v[94:95], v[130:131], v[94:95]
	v_pk_mul_f32 v[92:93], v[128:129], v[92:93]
	v_add_f32_e32 v158, v156, v157
	v_cvt_pk_bf16_f32 v92, v92, v93
	v_cvt_pk_bf16_f32 v93, v94, v95
	v_lshlrev_b64 v[94:95], 1, v[164:165]
	v_lshl_add_u64 v[156:157], s[14:15], 0, v[94:95]
	v_pk_add_f32 v[90:91], v[90:91], v[154:155]
	v_pk_add_f32 v[88:89], v[88:89], v[152:153]
	global_store_dwordx2 v[156:157], v[92:93], off
	v_mul_f32_e32 v92, v89, v89
	v_mul_f32_e32 v93, v91, v91
	global_store_dwordx4 v[194:195], v[88:91], off offset:64
	v_fmac_f32_e32 v92, v88, v88
	v_fmac_f32_e32 v93, v90, v90
	v_pk_mul_f32 v[90:91], v[122:123], v[90:91]
	v_pk_mul_f32 v[88:89], v[120:121], v[88:89]
	v_pk_add_f32 v[86:87], v[86:87], v[150:151]
	v_cvt_pk_bf16_f32 v88, v88, v89
	v_cvt_pk_bf16_f32 v89, v90, v91
	v_or_b32_e32 v90, 32, v94
	v_mov_b32_e32 v91, v95
	v_lshl_add_u64 v[90:91], s[14:15], 0, v[90:91]
	v_pk_add_f32 v[84:85], v[84:85], v[148:149]
	global_store_dwordx2 v[90:91], v[88:89], off
	v_mul_f32_e32 v88, v85, v85
	v_mul_f32_e32 v89, v87, v87
	global_store_dwordx4 v[194:195], v[84:87], off offset:512
	v_fmac_f32_e32 v88, v84, v84
	v_fmac_f32_e32 v89, v86, v86
	v_pk_mul_f32 v[86:87], v[118:119], v[86:87]
	v_pk_mul_f32 v[84:85], v[116:117], v[84:85]
	v_pk_add_f32 v[82:83], v[82:83], v[146:147]
	v_cvt_pk_bf16_f32 v84, v84, v85
	v_cvt_pk_bf16_f32 v85, v86, v87
	v_or_b32_e32 v86, 0x100, v94
	v_mov_b32_e32 v87, v95
	v_lshl_add_u64 v[86:87], s[14:15], 0, v[86:87]
	v_pk_add_f32 v[80:81], v[80:81], v[144:145]
	v_add_f32_e32 v92, v92, v93
	global_store_dwordx2 v[86:87], v[84:85], off
	v_mul_f32_e32 v84, v81, v81
	v_mul_f32_e32 v85, v83, v83
	v_add_f32_e32 v92, v158, v92
	v_add_f32_e32 v88, v88, v89
	v_fmac_f32_e32 v84, v80, v80
	v_fmac_f32_e32 v85, v82, v82
	v_add_f32_e32 v88, v92, v88
	v_add_f32_e32 v84, v84, v85
	v_add_f32_e32 v85, v88, v84
	ds_bpermute_b32 v86, v214, v85
	global_store_dwordx4 v[194:195], v[80:83], off offset:576
	v_or_b32_e32 v94, 0x120, v94
	v_readlane_b32 s61, v252, 17
	v_pk_mul_f32 v[80:81], v[112:113], v[80:81]
	v_pk_mul_f32 v[82:83], v[114:115], v[82:83]
	v_cvt_pk_bf16_f32 v84, v80, v81
	s_waitcnt lgkmcnt(0)
	v_add_f32_e32 v80, v85, v86
	ds_bpermute_b32 v81, v213, v80
	v_cvt_pk_bf16_f32 v85, v82, v83
	v_lshl_add_u64 v[82:83], s[14:15], 0, v[94:95]
	v_readlane_b32 s62, v252, 18
	v_readlane_b32 s63, v252, 19
	v_readlane_b32 s64, v252, 20
	v_readlane_b32 s65, v252, 21
	v_readlane_b32 s66, v252, 22
	v_readlane_b32 s67, v252, 23
	v_readlane_b32 s68, v252, 24
	v_readlane_b32 s69, v252, 25
	v_readlane_b32 s70, v252, 26
	v_readlane_b32 s71, v252, 27
	v_readlane_b32 s72, v252, 28
	v_readlane_b32 s73, v252, 29
	global_store_dwordx2 v[82:83], v[84:85], off
	s_and_saveexec_b64 s[28:29], s[2:3]
	s_cbranch_execz .LBB0_858
	v_lshl_add_u64 v[82:83], v[192:193], 2, s[16:17]
	s_waitcnt lgkmcnt(0)
	v_add_f32_e32 v80, v80, v81
	global_atomic_add_f32 v[82:83], v80, off

.LBB0_1060:
	v_readlane_b32 s60, v252, 16
	v_lshl_add_u32 v64, s54, 8, v218
	v_readlane_b32 s61, v252, 17
	v_readlane_b32 s62, v252, 18
	v_readlane_b32 s63, v252, 19
	v_readlane_b32 s72, v252, 28
	v_readlane_b32 s73, v252, 29
	v_lshl_or_b32 v144, s55, 8, v221
	v_ashrrev_i32_e32 v65, 31, v64
	v_readlane_b32 s74, v252, 30
	v_readlane_b32 s75, v252, 31
	s_mov_b64 s[60:61], s[72:73]
	v_ashrrev_i32_e32 v145, 31, v144
	s_waitcnt lgkmcnt(0)
	v_lshlrev_b64 v[0:1], 13, v[64:65]
	s_mov_b64 s[62:63], s[74:75]
	v_lshlrev_b64 v[16:17], 2, v[144:145]
	v_lshl_add_u64 v[210:211], s[62:63], 0, v[0:1]
	v_readlane_b32 s66, v252, 22
	v_readlane_b32 s67, v252, 23
	v_lshl_add_u64 v[228:229], v[210:211], 0, v[16:17]
	s_mov_b64 s[54:55], s[66:67]
	global_load_dwordx4 v[28:31], v[228:229], off
	global_load_dwordx4 v[40:43], v[228:229], off offset:64
	global_load_dwordx4 v[52:55], v[228:229], off offset:512
	v_lshl_add_u64 v[0:1], s[54:55], 0, v[16:17]
	global_load_dwordx4 v[12:15], v[0:1], off
	global_load_dwordx4 v[8:11], v[0:1], off offset:64
	global_load_dwordx4 v[4:7], v[0:1], off offset:512
	global_load_dwordx4 v[60:63], v[228:229], off offset:576
	v_or_b32_e32 v66, 16, v64
	v_or_b32_e32 v212, 32, v64
	v_ashrrev_i32_e32 v67, 31, v66
	v_ashrrev_i32_e32 v213, 31, v212
	v_lshlrev_b64 v[18:19], 13, v[66:67]
	v_lshlrev_b64 v[20:21], 13, v[212:213]
	v_lshl_add_u64 v[18:19], s[62:63], 0, v[18:19]
	global_load_dwordx4 v[0:3], v[0:1], off offset:576
	v_lshl_add_u64 v[20:21], s[62:63], 0, v[20:21]
	v_lshl_add_u64 v[216:217], v[18:19], 0, v[16:17]
	v_lshl_add_u64 v[214:215], v[20:21], 0, v[16:17]
	global_load_dwordx4 v[56:59], v[216:217], off
	global_load_dwordx4 v[48:51], v[216:217], off offset:64
	global_load_dwordx4 v[36:39], v[216:217], off offset:512
	global_load_dwordx4 v[24:27], v[216:217], off offset:576
	global_load_dwordx4 v[44:47], v[214:215], off
	global_load_dwordx4 v[32:35], v[214:215], off offset:64
	global_load_dwordx4 v[20:23], v[214:215], off offset:512
	global_load_dwordx4 v[16:19], v[214:215], off offset:576
	v_and_b32_e32 v227, 64, v225
	v_xor_b32_e32 v226, 16, v225
	v_add_u32_e32 v227, 64, v227
	v_xor_b32_e32 v230, 32, v225
	v_cmp_lt_i32_e32 vcc, v226, v227
	v_readlane_b32 s64, v252, 20
	v_readlane_b32 s65, v252, 21
	v_cndmask_b32_e32 v226, v225, v226, vcc
	v_cmp_lt_i32_e32 vcc, v230, v227
	v_lshlrev_b32_e32 v227, 2, v226
	v_readlane_b32 s68, v252, 24
	v_cndmask_b32_e32 v232, v225, v230, vcc
	v_lshlrev_b64 v[230:231], 11, v[64:65]
	v_lshl_add_u64 v[230:231], v[230:231], 0, v[144:145]
	v_lshlrev_b64 v[230:231], 1, v[230:231]
	v_lshlrev_b32_e32 v226, 2, v232
	v_lshl_add_u64 v[232:233], s[12:13], 0, v[230:231]
	v_or_b32_e32 v234, 32, v230
	v_mov_b32_e32 v235, v231
	v_lshl_add_u64 v[234:235], s[12:13], 0, v[234:235]
	v_readlane_b32 s69, v252, 25
	v_readlane_b32 s70, v252, 26
	v_readlane_b32 s71, v252, 27
	s_waitcnt vmcnt(8)
	v_pk_add_f32 v[30:31], v[198:199], v[30:31]
	v_pk_add_f32 v[28:29], v[200:201], v[28:29]
	v_pk_add_f32 v[42:43], v[202:203], v[42:43]
	v_pk_add_f32 v[40:41], v[204:205], v[40:41]
	v_pk_add_f32 v[54:55], v[208:209], v[54:55]
	v_pk_add_f32 v[52:53], v[206:207], v[52:53]
	v_mul_f32_e32 v236, v29, v29
	v_mul_f32_e32 v237, v31, v31
	v_pk_mul_f32 v[198:199], v[14:15], v[30:31]
	v_pk_mul_f32 v[200:201], v[12:13], v[28:29]
	v_mul_f32_e32 v238, v41, v41
	v_mul_f32_e32 v239, v43, v43
	global_store_dwordx4 v[228:229], v[28:31], off
	v_mul_f32_e32 v240, v53, v53
	v_mul_f32_e32 v241, v55, v55
	v_fmac_f32_e32 v236, v28, v28
	v_fmac_f32_e32 v237, v30, v30
	v_cvt_pk_bf16_f32 v28, v200, v201
	v_cvt_pk_bf16_f32 v29, v198, v199
	v_fmac_f32_e32 v238, v40, v40
	v_fmac_f32_e32 v239, v42, v42
	v_fmac_f32_e32 v240, v52, v52
	v_fmac_f32_e32 v241, v54, v54
	v_add_f32_e32 v199, v236, v237
	global_store_dwordx2 v[232:233], v[28:29], off
	global_store_dwordx4 v[228:229], v[40:43], off offset:64
	v_add_f32_e32 v28, v238, v239
	v_add_f32_e32 v29, v240, v241
	v_add_f32_e32 v28, v199, v28
	v_pk_mul_f32 v[202:203], v[10:11], v[42:43]
	v_pk_mul_f32 v[204:205], v[8:9], v[40:41]
	v_pk_mul_f32 v[206:207], v[6:7], v[54:55]
	v_pk_mul_f32 v[208:209], v[4:5], v[52:53]
	v_add_f32_e32 v40, v28, v29
	v_or_b32_e32 v28, 0x100, v230
	v_mov_b32_e32 v29, v231
	v_cvt_pk_bf16_f32 v30, v204, v205
	v_cvt_pk_bf16_f32 v31, v202, v203
	v_cvt_pk_bf16_f32 v198, v208, v209
	v_cvt_pk_bf16_f32 v199, v206, v207
	v_lshl_add_u64 v[28:29], s[12:13], 0, v[28:29]
	global_store_dwordx2 v[234:235], v[30:31], off
	global_store_dwordx4 v[228:229], v[52:55], off offset:512
	global_store_dwordx2 v[28:29], v[198:199], off
	v_pk_add_f32 v[30:31], v[196:197], v[62:63]
	v_pk_add_f32 v[28:29], v[194:195], v[60:61]
	v_mul_f32_e32 v42, v31, v31
	v_mul_f32_e32 v41, v29, v29
	v_fmac_f32_e32 v41, v28, v28
	v_fmac_f32_e32 v42, v30, v30
	v_add_f32_e32 v41, v41, v42
	v_add_f32_e32 v41, v40, v41
	ds_bpermute_b32 v42, v227, v41
	global_store_dwordx4 v[228:229], v[28:31], off offset:576
	v_or_b32_e32 v230, 0x120, v230
	s_nop 0
	v_pk_mul_f32 v[28:29], v[0:1], v[28:29]
	v_pk_mul_f32 v[30:31], v[2:3], v[30:31]
	v_cvt_pk_bf16_f32 v40, v28, v29
	s_waitcnt lgkmcnt(0)
	v_add_f32_e32 v28, v41, v42
	ds_bpermute_b32 v29, v226, v28
	v_cvt_pk_bf16_f32 v41, v30, v31
	v_lshl_add_u64 v[30:31], s[12:13], 0, v[230:231]
	global_store_dwordx2 v[30:31], v[40:41], off
	s_and_saveexec_b64 s[24:25], s[2:3]
	s_cbranch_execz .LBB0_1062
	v_lshl_add_u64 v[30:31], v[64:65], 2, s[14:15]
	s_waitcnt lgkmcnt(0)
	v_add_f32_e32 v28, v28, v29
	global_atomic_add_f32 v[30:31], v28, off
.LBB0_1062:
	s_or_b64 exec, exec, s[24:25]
	v_or_b32_e32 v194, 48, v64
	v_ashrrev_i32_e32 v195, 31, v194
	v_readlane_b32 s60, v252, 16
	s_waitcnt lgkmcnt(0)
	v_lshlrev_b64 v[28:29], 13, v[194:195]
	v_readlane_b32 s74, v252, 30
	v_readlane_b32 s75, v252, 31
	s_waitcnt vmcnt(12)
	v_pk_add_f32 v[58:59], v[192:193], v[58:59]
	v_pk_add_f32 v[56:57], v[190:191], v[56:57]
	v_lshl_add_u64 v[28:29], s[74:75], 0, v[28:29]
	v_lshl_add_u64 v[196:197], v[144:145], 2, v[28:29]
	global_load_dwordx4 v[60:63], v[196:197], off
	global_load_dwordx4 v[52:55], v[196:197], off offset:64
	global_load_dwordx4 v[40:43], v[196:197], off offset:512
	global_load_dwordx4 v[28:31], v[196:197], off offset:576
	v_lshlrev_b64 v[198:199], 11, v[66:67]
	v_mul_f32_e32 v65, v57, v57
	v_mul_f32_e32 v190, v59, v59
	v_lshl_add_u64 v[198:199], v[198:199], 0, v[144:145]
	global_store_dwordx4 v[216:217], v[56:59], off
	v_fmac_f32_e32 v65, v56, v56
	v_fmac_f32_e32 v190, v58, v58
	v_pk_mul_f32 v[58:59], v[14:15], v[58:59]
	v_pk_mul_f32 v[56:57], v[12:13], v[56:57]
	v_add_f32_e32 v65, v65, v190
	v_cvt_pk_bf16_f32 v56, v56, v57
	v_cvt_pk_bf16_f32 v57, v58, v59
	v_lshlrev_b64 v[58:59], 1, v[198:199]
	v_lshl_add_u64 v[190:191], s[12:13], 0, v[58:59]
	v_pk_add_f32 v[50:51], v[188:189], v[50:51]
	v_pk_add_f32 v[48:49], v[186:187], v[48:49]
	global_store_dwordx2 v[190:191], v[56:57], off
	v_mul_f32_e32 v56, v49, v49
	v_mul_f32_e32 v57, v51, v51
	global_store_dwordx4 v[216:217], v[48:51], off offset:64
	v_fmac_f32_e32 v56, v48, v48
	v_fmac_f32_e32 v57, v50, v50
	v_pk_mul_f32 v[50:51], v[10:11], v[50:51]
	v_pk_mul_f32 v[48:49], v[8:9], v[48:49]
	v_pk_add_f32 v[38:39], v[184:185], v[38:39]
	v_cvt_pk_bf16_f32 v48, v48, v49
	v_cvt_pk_bf16_f32 v49, v50, v51
	v_or_b32_e32 v50, 32, v58
	v_mov_b32_e32 v51, v59
	v_lshl_add_u64 v[50:51], s[12:13], 0, v[50:51]
	v_pk_add_f32 v[36:37], v[182:183], v[36:37]
	global_store_dwordx2 v[50:51], v[48:49], off
	v_mul_f32_e32 v48, v37, v37
	v_mul_f32_e32 v49, v39, v39
	global_store_dwordx4 v[216:217], v[36:39], off offset:512
	v_fmac_f32_e32 v48, v36, v36
	v_fmac_f32_e32 v49, v38, v38
	v_pk_mul_f32 v[38:39], v[6:7], v[38:39]
	v_pk_mul_f32 v[36:37], v[4:5], v[36:37]
	v_pk_add_f32 v[26:27], v[180:181], v[26:27]
	v_cvt_pk_bf16_f32 v36, v36, v37
	v_cvt_pk_bf16_f32 v37, v38, v39
	v_or_b32_e32 v38, 0x100, v58
	v_mov_b32_e32 v39, v59
	v_lshl_add_u64 v[38:39], s[12:13], 0, v[38:39]
	v_pk_add_f32 v[24:25], v[178:179], v[24:25]
	v_add_f32_e32 v56, v56, v57
	global_store_dwordx2 v[38:39], v[36:37], off
	v_mul_f32_e32 v36, v25, v25
	v_mul_f32_e32 v37, v27, v27
	v_add_f32_e32 v56, v65, v56
	v_add_f32_e32 v48, v48, v49
	v_fmac_f32_e32 v36, v24, v24
	v_fmac_f32_e32 v37, v26, v26
	v_add_f32_e32 v48, v56, v48
	v_add_f32_e32 v36, v36, v37
	v_add_f32_e32 v37, v48, v36
	ds_bpermute_b32 v38, v227, v37
	global_store_dwordx4 v[216:217], v[24:27], off offset:576
	v_or_b32_e32 v58, 0x120, v58
	v_readlane_b32 s61, v252, 17
	v_pk_mul_f32 v[24:25], v[0:1], v[24:25]
	v_pk_mul_f32 v[26:27], v[2:3], v[26:27]
	v_cvt_pk_bf16_f32 v36, v24, v25
	s_waitcnt lgkmcnt(0)
	v_add_f32_e32 v24, v37, v38
	ds_bpermute_b32 v25, v226, v24
	v_cvt_pk_bf16_f32 v37, v26, v27
	v_lshl_add_u64 v[26:27], s[12:13], 0, v[58:59]
	v_readlane_b32 s62, v252, 18
	v_readlane_b32 s63, v252, 19
	v_readlane_b32 s64, v252, 20
	v_readlane_b32 s65, v252, 21
	v_readlane_b32 s66, v252, 22
	v_readlane_b32 s67, v252, 23
	v_readlane_b32 s68, v252, 24
	v_readlane_b32 s69, v252, 25
	v_readlane_b32 s70, v252, 26
	v_readlane_b32 s71, v252, 27
	v_readlane_b32 s72, v252, 28
	v_readlane_b32 s73, v252, 29
	global_store_dwordx2 v[26:27], v[36:37], off
	s_and_saveexec_b64 s[24:25], s[2:3]
	s_cbranch_execz .LBB0_1064
	v_lshl_add_u64 v[26:27], v[66:67], 2, s[14:15]
	s_waitcnt lgkmcnt(0)
	v_add_f32_e32 v24, v24, v25
	global_atomic_add_f32 v[26:27], v24, off
.LBB0_1064:
	s_or_b64 exec, exec, s[24:25]
	v_add_u32_e32 v178, 0x80, v64
	v_ashrrev_i32_e32 v179, 31, v178
	v_readlane_b32 s60, v252, 16
	s_waitcnt lgkmcnt(0)
	v_lshlrev_b64 v[24:25], 13, v[178:179]
	v_readlane_b32 s74, v252, 30
	v_readlane_b32 s75, v252, 31
	s_waitcnt vmcnt(20)
	v_pk_add_f32 v[46:47], v[176:177], v[46:47]
	v_pk_add_f32 v[44:45], v[174:175], v[44:45]
	v_lshl_add_u64 v[24:25], s[74:75], 0, v[24:25]
	v_lshl_add_u64 v[180:181], v[144:145], 2, v[24:25]
	global_load_dwordx4 v[64:67], v[180:181], off
	global_load_dwordx4 v[48:51], v[180:181], off offset:64
	global_load_dwordx4 v[36:39], v[180:181], off offset:512
	global_load_dwordx4 v[24:27], v[180:181], off offset:576
	v_lshlrev_b64 v[56:57], 11, v[212:213]
	v_mul_f32_e32 v58, v45, v45
	v_mul_f32_e32 v59, v47, v47
	v_lshl_add_u64 v[56:57], v[56:57], 0, v[144:145]
	global_store_dwordx4 v[214:215], v[44:47], off
	v_fmac_f32_e32 v58, v44, v44
	v_fmac_f32_e32 v59, v46, v46
	v_pk_mul_f32 v[46:47], v[14:15], v[46:47]
	v_pk_mul_f32 v[44:45], v[12:13], v[44:45]
	v_pk_add_f32 v[34:35], v[172:173], v[34:35]
	v_cvt_pk_bf16_f32 v44, v44, v45
	v_cvt_pk_bf16_f32 v45, v46, v47
	v_lshlrev_b64 v[46:47], 1, v[56:57]
	v_lshl_add_u64 v[56:57], s[12:13], 0, v[46:47]
	v_pk_add_f32 v[32:33], v[170:171], v[32:33]
	global_store_dwordx2 v[56:57], v[44:45], off
	v_mul_f32_e32 v44, v33, v33
	v_mul_f32_e32 v45, v35, v35
	global_store_dwordx4 v[214:215], v[32:35], off offset:64
	v_fmac_f32_e32 v44, v32, v32
	v_fmac_f32_e32 v45, v34, v34
	v_pk_mul_f32 v[34:35], v[10:11], v[34:35]
	v_pk_mul_f32 v[32:33], v[8:9], v[32:33]
	v_pk_add_f32 v[22:23], v[168:169], v[22:23]
	v_cvt_pk_bf16_f32 v32, v32, v33
	v_cvt_pk_bf16_f32 v33, v34, v35
	v_or_b32_e32 v34, 32, v46
	v_mov_b32_e32 v35, v47
	v_lshl_add_u64 v[34:35], s[12:13], 0, v[34:35]
	v_pk_add_f32 v[20:21], v[166:167], v[20:21]
	global_store_dwordx2 v[34:35], v[32:33], off
	v_mul_f32_e32 v32, v21, v21
	v_mul_f32_e32 v33, v23, v23
	global_store_dwordx4 v[214:215], v[20:23], off offset:512
	v_fmac_f32_e32 v32, v20, v20
	v_fmac_f32_e32 v33, v22, v22
	v_pk_mul_f32 v[22:23], v[6:7], v[22:23]
	v_pk_mul_f32 v[20:21], v[4:5], v[20:21]
	v_pk_add_f32 v[18:19], v[164:165], v[18:19]
	v_cvt_pk_bf16_f32 v20, v20, v21
	v_cvt_pk_bf16_f32 v21, v22, v23
	v_or_b32_e32 v22, 0x100, v46
	v_mov_b32_e32 v23, v47
	v_lshl_add_u64 v[22:23], s[12:13], 0, v[22:23]
	v_pk_add_f32 v[16:17], v[162:163], v[16:17]
	v_add_f32_e32 v58, v58, v59
	v_add_f32_e32 v44, v44, v45
	global_store_dwordx2 v[22:23], v[20:21], off
	v_mul_f32_e32 v20, v17, v17
	v_mul_f32_e32 v21, v19, v19
	v_add_f32_e32 v44, v58, v44
	v_add_f32_e32 v32, v32, v33
	v_fmac_f32_e32 v20, v16, v16
	v_fmac_f32_e32 v21, v18, v18
	v_add_f32_e32 v32, v44, v32
	v_add_f32_e32 v20, v20, v21
	v_add_f32_e32 v21, v32, v20
	ds_bpermute_b32 v22, v227, v21
	global_store_dwordx4 v[214:215], v[16:19], off offset:576
	v_or_b32_e32 v46, 0x120, v46
	v_readlane_b32 s61, v252, 17
	v_pk_mul_f32 v[16:17], v[0:1], v[16:17]
	v_pk_mul_f32 v[18:19], v[2:3], v[18:19]
	v_cvt_pk_bf16_f32 v20, v16, v17
	s_waitcnt lgkmcnt(0)
	v_add_f32_e32 v16, v21, v22
	ds_bpermute_b32 v17, v226, v16
	v_cvt_pk_bf16_f32 v21, v18, v19
	v_lshl_add_u64 v[18:19], s[12:13], 0, v[46:47]
	v_readlane_b32 s62, v252, 18
	v_readlane_b32 s63, v252, 19
	v_readlane_b32 s64, v252, 20
	v_readlane_b32 s65, v252, 21
	v_readlane_b32 s66, v252, 22
	v_readlane_b32 s67, v252, 23
	v_readlane_b32 s68, v252, 24
	v_readlane_b32 s69, v252, 25
	v_readlane_b32 s70, v252, 26
	v_readlane_b32 s71, v252, 27
	v_readlane_b32 s72, v252, 28
	v_readlane_b32 s73, v252, 29
	global_store_dwordx2 v[18:19], v[20:21], off
	s_and_saveexec_b64 s[24:25], s[2:3]
	s_cbranch_execz .LBB0_1066
	v_lshl_add_u64 v[18:19], v[212:213], 2, s[14:15]
	s_waitcnt lgkmcnt(0)
	v_add_f32_e32 v16, v16, v17
	global_atomic_add_f32 v[18:19], v16, off
